# norm phases: wave v takes rows l0+8v+k instead of l0+v+8k (rows 16 apart touched together: DRAM page locality)
# baseline (speedup 1.0000x reference)
; #define LAS __attribute__((address_space(3)))
; __device__ __forceinline__ void norm_mod_phase(Frame& F, int L, const float* gvec, int sh_chunk, int nrows, const float* pg, const float* pg2, const float* xlat, const float* xctx) {
;     ...
;     const int lane = F.lane, nl = l1 - l0, ntot = nl + (c1 - c0);
;     for (int i = F.wave; i < ntot; i += NWAVES) {
;         const int r = i < nl ? l0 + i : c0 + (i - nl);
;         const LAS f32x4* vq = (const LAS f32x4*)(V + (size_t)(r < MLAT ? (r >> 11) - b0 : 2) * 4 * D) + lane;
;         f32x4 v[8]; float ss = 0.f;
;         const bool lat = r < MLAT, xbf = lat ? (xlat == nullptr) : (xctx == nullptr);
;         const bool h1 = pg != nullptr && lat, h2 = pg2 != nullptr && lat, hc = pg != nullptr && !lat;
;         u32x4 xraw[8]; u32x2 aux[4][8];
;         if (xbf) { const u32x2* xb = (const u32x2*)((const bf16_t*)(F.ws + (lat ? WS_XB : WS_XC)) + (size_t)(lat ? r : r - MLAT) * D) + lane;
; #pragma unroll
;             for (int j = 0; j < 8; ++j) { const u32x2 w = __builtin_nontemporal_load(xb + 64 * j); xraw[j].x = w.x; xraw[j].y = w.y; }
;         } else { const u32x4* xr = (const u32x4*)(lat ? xlat + (size_t)r * D : xctx + (size_t)(r - MLAT) * D) + lane;
; #pragma unroll
;             for (int j = 0; j < 8; ++j) xraw[j] = __builtin_nontemporal_load(xr + 64 * j); }
.LBB0_212:
	s_and_b32 s100, s26, 7
	s_lshl_b32 s100, s100, 3
	s_lshr_b32 s101, s26, 3
	s_or_b32 s100, s100, s101
	v_readlane_b32 s4, v254, 45
	s_cmp_eq_u32 s4, 64
	s_cselect_b32 s100, s100, s26
	s_cmp_lt_i32 s26, s4
	s_cselect_b32 s100, s100, s26
	v_readlane_b32 s4, v254, 41
	v_readlane_b32 s5, v254, 46
	s_cselect_b32 s4, s4, s5
	s_add_i32 s10, s4, s100
	s_cmpk_lt_i32 s10, 0x4000
	s_cselect_b64 s[28:29], -1, 0
	s_and_b64 s[4:5], s[28:29], exec
	s_cselect_b32 s5, s6, s14
	s_cselect_b32 s4, s7, s15
	s_cmp_lg_u64 s[4:5], 0
	s_cselect_b64 s[30:31], -1, 0
	s_and_b64 vcc, exec, s[30:31]
	s_cbranch_vccz .LBB0_230
	s_add_i32 s11, s10, 0xffffc000
	s_ashr_i32 s36, s10, 31
	s_and_b64 s[34:35], s[28:29], exec
	s_cselect_b32 s35, s36, 0
	s_cselect_b32 s34, s10, s11
	s_lshl_b64 s[34:35], s[34:35], 13
	s_add_u32 s4, s4, s34
	s_addc_u32 s5, s5, s35
	v_lshl_add_u64 v[16:17], v[64:65], 4, s[4:5]
	s_movk_i32 s4, 0x1000
	v_add_co_u32_e32 v28, vcc, s4, v16
	global_load_dwordx4 v[0:3], v[16:17], off nt
	global_load_dwordx4 v[4:7], v[16:17], off offset:1024 nt
	global_load_dwordx4 v[8:11], v[16:17], off offset:2048 nt
	global_load_dwordx4 v[12:15], v[16:17], off offset:3072 nt
	v_addc_co_u32_e32 v29, vcc, 0, v17, vcc
	global_load_dwordx4 v[16:19], v[28:29], off nt
	global_load_dwordx4 v[20:23], v[28:29], off offset:1024 nt
	global_load_dwordx4 v[24:27], v[28:29], off offset:2048 nt
	s_nop 0
	global_load_dwordx4 v[28:31], v[28:29], off offset:3072 nt
	s_cbranch_execnz .LBB0_215

; #define LAS __attribute__((address_space(3)))
; __device__ __forceinline__ void norm_mod_phase(Frame& F, int L, const float* gvec, int sh_chunk, int nrows, const float* pg, const float* pg2, const float* xlat, const float* xctx) {
;     ...
;     const int lane = F.lane, nl = l1 - l0, ntot = nl + (c1 - c0);
;     for (int i = F.wave; i < ntot; i += NWAVES) {
;         const int r = i < nl ? l0 + i : c0 + (i - nl);
;         const LAS f32x4* vq = (const LAS f32x4*)(V + (size_t)(r < MLAT ? (r >> 11) - b0 : 2) * 4 * D) + lane;
;         f32x4 v[8]; float ss = 0.f;
;         const bool lat = r < MLAT, xbf = lat ? (xlat == nullptr) : (xctx == nullptr);
;         const bool h1 = pg != nullptr && lat, h2 = pg2 != nullptr && lat, hc = pg != nullptr && !lat;
;         u32x4 xraw[8]; u32x2 aux[4][8];
;         if (xbf) { const u32x2* xb = (const u32x2*)((const bf16_t*)(F.ws + (lat ? WS_XB : WS_XC)) + (size_t)(lat ? r : r - MLAT) * D) + lane;
; #pragma unroll
;             for (int j = 0; j < 8; ++j) { const u32x2 w = __builtin_nontemporal_load(xb + 64 * j); xraw[j].x = w.x; xraw[j].y = w.y; }
;         } else { const u32x4* xr = (const u32x4*)(lat ? xlat + (size_t)r * D : xctx + (size_t)(r - MLAT) * D) + lane;
; #pragma unroll
;             for (int j = 0; j < 8; ++j) xraw[j] = __builtin_nontemporal_load(xr + 64 * j); }
.LBB0_1042:
	s_and_b32 s100, s41, 7
	s_lshl_b32 s100, s100, 3
	s_lshr_b32 s101, s41, 3
	s_or_b32 s100, s100, s101
	v_readlane_b32 s0, v254, 45
	s_cmp_eq_u32 s0, 64
	s_cselect_b32 s100, s100, s41
	s_cmp_lt_i32 s41, s0
	s_cselect_b32 s100, s100, s41
	v_readlane_b32 s0, v254, 41
	s_cselect_b32 s0, s0, s40
	s_add_i32 s0, s0, s100
	s_cmpk_lt_i32 s0, 0x4000
	s_cselect_b64 s[34:35], -1, 0
	s_cmpk_gt_i32 s0, 0x3fff
	s_cselect_b64 s[10:11], -1, 0
	s_and_b64 s[4:5], s[10:11], exec
	s_cselect_b32 s5, s15, s7
	s_cselect_b32 s4, s26, s14
	s_cmp_lg_u64 s[4:5], 0
	s_cselect_b64 s[30:31], -1, 0
	s_and_b64 vcc, exec, s[30:31]
	s_cbranch_vccz .LBB0_1057
	s_add_i32 s1, s0, 0xffffc000
	s_ashr_i32 s17, s0, 31
	s_and_b64 s[36:37], s[10:11], exec
	s_cselect_b32 s37, 0, s17
	s_cselect_b32 s36, s1, s0
	s_lshl_b64 s[36:37], s[36:37], 13
	s_add_u32 s4, s4, s36
	s_addc_u32 s5, s5, s37
	v_lshl_add_u64 v[16:17], v[64:65], 4, s[4:5]
	s_movk_i32 s1, 0x1000
	v_add_co_u32_e32 v28, vcc, s1, v16
	global_load_dwordx4 v[0:3], v[16:17], off nt
	global_load_dwordx4 v[4:7], v[16:17], off offset:1024 nt
	global_load_dwordx4 v[8:11], v[16:17], off offset:2048 nt
	global_load_dwordx4 v[12:15], v[16:17], off offset:3072 nt
	v_addc_co_u32_e32 v29, vcc, 0, v17, vcc
	global_load_dwordx4 v[16:19], v[28:29], off nt
	global_load_dwordx4 v[20:23], v[28:29], off offset:1024 nt
	global_load_dwordx4 v[24:27], v[28:29], off offset:2048 nt
	s_nop 0
	global_load_dwordx4 v[28:31], v[28:29], off offset:3072 nt
	s_cbranch_execnz .LBB0_1045
